# diff-attention flash loop: moved next-tile LDS write + global prefetch (W) from iteration top to after QK MFMA issue
# speedup vs baseline: 1.0035x; 1.0035x over previous
.LBB0_362:
	v_cmp_le_i32_e32 vcc, s94, v229
	s_and_saveexec_b64 s[12:13], vcc
	s_cbranch_execz .Lwl_skip1
	s_bitcmp1_b32 s26, 0
	s_cselect_b32 s0, 0x6c00, 0
	s_add_i32 s0, s0, 0
	v_add_u32_e32 v0, s0, v232
	v_add_u32_e32 v180, v0, v238
	ds_read_b128 v[66:69], v180
	ds_read_b128 v[150:153], v180 offset:32
	ds_read_b128 v[70:73], v180 offset:4608
	ds_read_b128 v[154:157], v180 offset:4640
	s_waitcnt lgkmcnt(3)
	v_mfma_f32_32x32x16_bf16 v[82:97], v[66:69], v[98:101], 0
	s_waitcnt lgkmcnt(1)
	v_mfma_f32_32x32x16_bf16 v[66:81], v[70:73], v[98:101], 0
	v_mfma_f32_32x32x16_bf16 v[82:97], v[150:153], v[102:105], v[82:97]
	ds_read_b128 v[150:153], v180 offset:64
	ds_read_b128 v[158:161], v180 offset:96
	ds_read_b128 v[162:165], v180 offset:4672
	ds_read_b128 v[180:183], v180 offset:4704
	s_waitcnt lgkmcnt(4)
	v_mfma_f32_32x32x16_bf16 v[66:81], v[154:157], v[102:105], v[66:81]
	s_waitcnt lgkmcnt(3)
	v_mfma_f32_32x32x16_bf16 v[82:97], v[150:153], v[106:109], v[82:97]
	v_add_u32_e32 v242, v0, v233
	s_waitcnt lgkmcnt(1)
	v_mfma_f32_32x32x16_bf16 v[66:81], v[162:165], v[106:109], v[66:81]
	v_mfma_f32_32x32x16_bf16 v[82:97], v[158:161], v[110:113], v[82:97]
	ds_read_b128 v[162:165], v242 offset:9216
	ds_read_b128 v[158:161], v242 offset:13824
	ds_read_b128 v[154:157], v242 offset:18432
	ds_read_b128 v[150:153], v242 offset:23040
	s_waitcnt lgkmcnt(4)
	v_mfma_f32_32x32x16_bf16 v[66:81], v[180:183], v[110:113], v[66:81]
	s_cmp_ge_u32 s27, s22
	s_cbranch_scc1 .Lwl_q1
	s_bitcmp1_b32 s27, 0
	s_cselect_b32 s98, 0x6c00, 0
	v_add_u32_e32 v204, s98, v239
	s_waitcnt vmcnt(2)
	ds_write_b128 v204, v[126:129]
	v_add_u32_e32 v204, s98, v234
	v_add_u32_e32 v205, v204, v235
	v_add_u32_e32 v204, v204, v237
	s_cmp_ge_u32 s26, s21
	s_waitcnt vmcnt(1)
	ds_write_b128 v205, v[118:121] offset:9216
	s_waitcnt vmcnt(0)
	ds_write_b128 v204, v[114:117] offset:9216
	s_cbranch_scc1 .Lwl_q1
	v_add_u32_e32 v204, s94, v231
	v_add_u32_e32 v204, 0x100, v204
	v_mad_i64_i32 v[206:207], s[98:99], v204, s87, v[168:169]
	v_lshl_add_u64 v[208:209], s[94:95], 1, v[170:171]
	v_lshl_add_u64 v[210:211], v[208:209], 0, v[172:173]
	global_load_dwordx4 v[126:129], v[206:207], off offset:2048
	global_load_dwordx4 v[118:121], v[210:211], off offset:512
	v_lshl_add_u64 v[206:207], v[208:209], 0, v[174:175]
	global_load_dwordx4 v[114:117], v[206:207], off offset:512
.Lwl_q1:
	s_movk_i32 s0, 0xbf
	v_add_u32_e32 v180, 0x80, v240
	v_add3_u32 v0, v236, v240, s0
	v_cmp_gt_i32_e32 vcc, s85, v180
	s_and_saveexec_b64 s[0:1], vcc
	s_xor_b64 s[0:1], exec, s[0:1]
	s_cbranch_execz .LBB0_365
	v_add_u32_e32 v181, -1, v0
	v_add_u32_e32 v182, 0x1fe, v0
	v_add_u32_e32 v183, 0x1fd, v0
	v_add_u32_e32 v184, 0x1fc, v0
	v_add_u32_e32 v185, 0x1fb, v0
	v_add_u32_e32 v186, 0x1fa, v0
	v_add_u32_e32 v187, 0x1f9, v0
	v_and_b32_e32 v180, 0x1ff, v0
	s_add_i32 s4, 0, 0x20100
	v_and_b32_e32 v181, 0x1ff, v181
	v_and_b32_e32 v182, 0x1ff, v182
	v_and_b32_e32 v183, 0x1ff, v183
	v_and_b32_e32 v184, 0x1ff, v184
	v_and_b32_e32 v185, 0x1ff, v185
	v_and_b32_e32 v186, 0x1ff, v186
	v_and_b32_e32 v187, 0x1ff, v187
	v_lshl_add_u32 v180, v180, 2, s4
	v_lshl_add_u32 v181, v181, 2, s4
	v_lshl_add_u32 v182, v182, 2, s4
	v_lshl_add_u32 v183, v183, 2, s4
	v_lshl_add_u32 v184, v184, 2, s4
	v_lshl_add_u32 v185, v185, 2, s4
	v_lshl_add_u32 v186, v186, 2, s4
	v_lshl_add_u32 v187, v187, 2, s4
	ds_read_b32 v180, v180
	ds_read_b32 v181, v181
	ds_read_b32 v182, v182
	ds_read_b32 v183, v183
	ds_read_b32 v184, v184
	ds_read_b32 v185, v185
	ds_read_b32 v186, v186
	ds_read_b32 v187, v187
	s_waitcnt lgkmcnt(6)
	v_pk_add_f32 v[180:181], v[180:181], v[178:179] op_sel_hi:[1,0] neg_lo:[0,1] neg_hi:[0,1]
	s_nop 0
	v_pk_fma_f32 v[180:181], v[82:83], s[82:83], v[180:181] op_sel_hi:[1,0,1]
	s_waitcnt lgkmcnt(4)
	v_pk_add_f32 v[82:83], v[182:183], v[178:179] op_sel_hi:[1,0] neg_lo:[0,1] neg_hi:[0,1]
	v_max3_f32 v188, v180, s33, v181
	v_pk_fma_f32 v[182:183], v[84:85], s[82:83], v[82:83] op_sel_hi:[1,0,1]
	s_waitcnt lgkmcnt(2)
	v_pk_add_f32 v[82:83], v[184:185], v[178:179] op_sel_hi:[1,0] neg_lo:[0,1] neg_hi:[0,1]
	v_max3_f32 v84, v188, v182, v183
	v_pk_fma_f32 v[184:185], v[86:87], s[82:83], v[82:83] op_sel_hi:[1,0,1]
	s_waitcnt lgkmcnt(0)
	v_pk_add_f32 v[82:83], v[186:187], v[178:179] op_sel_hi:[1,0] neg_lo:[0,1] neg_hi:[0,1]
	v_max3_f32 v84, v84, v184, v185
	v_pk_fma_f32 v[186:187], v[88:89], s[82:83], v[82:83] op_sel_hi:[1,0,1]
	v_add_u32_e32 v82, 0x1f0, v0
	v_max3_f32 v188, v84, v186, v187
	v_add_u32_e32 v83, 0x1ef, v0
	v_add_u32_e32 v84, 0x1ee, v0
	v_add_u32_e32 v85, 0x1ed, v0
	v_add_u32_e32 v86, 0x1ec, v0
	v_add_u32_e32 v87, 0x1eb, v0
	v_add_u32_e32 v88, 0x1ea, v0
	v_add_u32_e32 v89, 0x1e9, v0
	v_and_b32_e32 v82, 0x1ff, v82
	v_and_b32_e32 v83, 0x1ff, v83
	v_and_b32_e32 v84, 0x1ff, v84
	v_and_b32_e32 v85, 0x1ff, v85
	v_and_b32_e32 v86, 0x1ff, v86
	v_and_b32_e32 v87, 0x1ff, v87
	v_and_b32_e32 v88, 0x1ff, v88
	v_and_b32_e32 v89, 0x1ff, v89
	v_lshl_add_u32 v82, v82, 2, s4
	v_lshl_add_u32 v83, v83, 2, s4
	v_lshl_add_u32 v84, v84, 2, s4
	v_lshl_add_u32 v85, v85, 2, s4
	v_lshl_add_u32 v86, v86, 2, s4
	v_lshl_add_u32 v87, v87, 2, s4
	v_lshl_add_u32 v88, v88, 2, s4
	v_lshl_add_u32 v89, v89, 2, s4
	ds_read_b32 v82, v82
	ds_read_b32 v83, v83
	ds_read_b32 v84, v84
	ds_read_b32 v85, v85
	ds_read_b32 v86, v86
	ds_read_b32 v87, v87
	ds_read_b32 v88, v88
	ds_read_b32 v89, v89
	s_waitcnt lgkmcnt(6)
	v_pk_add_f32 v[82:83], v[82:83], v[178:179] op_sel_hi:[1,0] neg_lo:[0,1] neg_hi:[0,1]
	s_nop 0
	v_pk_fma_f32 v[192:193], v[90:91], s[82:83], v[82:83] op_sel_hi:[1,0,1]
	s_waitcnt lgkmcnt(4)
	v_pk_add_f32 v[82:83], v[84:85], v[178:179] op_sel_hi:[1,0] neg_lo:[0,1] neg_hi:[0,1]
	v_max3_f32 v90, v188, v192, v193
	v_pk_fma_f32 v[206:207], v[92:93], s[82:83], v[82:83] op_sel_hi:[1,0,1]
	s_waitcnt lgkmcnt(2)
	v_pk_add_f32 v[82:83], v[86:87], v[178:179] op_sel_hi:[1,0] neg_lo:[0,1] neg_hi:[0,1]
	v_max3_f32 v84, v90, v206, v207
	v_pk_fma_f32 v[188:189], v[94:95], s[82:83], v[82:83] op_sel_hi:[1,0,1]
	s_waitcnt lgkmcnt(0)
	v_pk_add_f32 v[82:83], v[88:89], v[178:179] op_sel_hi:[1,0] neg_lo:[0,1] neg_hi:[0,1]
	v_max3_f32 v84, v84, v188, v189
	v_pk_fma_f32 v[190:191], v[96:97], s[82:83], v[82:83] op_sel_hi:[1,0,1]
	v_add_u32_e32 v82, 0x1e0, v0
	v_max3_f32 v90, v84, v190, v191
	v_add_u32_e32 v83, 0x1df, v0
	v_add_u32_e32 v84, 0x1de, v0
	v_add_u32_e32 v85, 0x1dd, v0
	v_add_u32_e32 v86, 0x1dc, v0
	v_add_u32_e32 v87, 0x1db, v0
	v_add_u32_e32 v88, 0x1da, v0
	v_add_u32_e32 v89, 0x1d9, v0
	v_and_b32_e32 v82, 0x1ff, v82
	v_and_b32_e32 v83, 0x1ff, v83
	v_and_b32_e32 v84, 0x1ff, v84
	v_and_b32_e32 v85, 0x1ff, v85
	v_and_b32_e32 v86, 0x1ff, v86
	v_and_b32_e32 v87, 0x1ff, v87
	v_and_b32_e32 v88, 0x1ff, v88
	v_and_b32_e32 v89, 0x1ff, v89
	v_lshl_add_u32 v82, v82, 2, s4
	v_lshl_add_u32 v83, v83, 2, s4
	v_lshl_add_u32 v84, v84, 2, s4
	v_lshl_add_u32 v85, v85, 2, s4
	v_lshl_add_u32 v86, v86, 2, s4
	v_lshl_add_u32 v87, v87, 2, s4
	v_lshl_add_u32 v88, v88, 2, s4
	v_lshl_add_u32 v89, v89, 2, s4
	ds_read_b32 v82, v82
	ds_read_b32 v83, v83
	ds_read_b32 v84, v84
	ds_read_b32 v85, v85
	ds_read_b32 v86, v86
	ds_read_b32 v87, v87
	ds_read_b32 v88, v88
	ds_read_b32 v89, v89
	s_waitcnt lgkmcnt(6)
	v_pk_add_f32 v[82:83], v[82:83], v[178:179] op_sel_hi:[1,0] neg_lo:[0,1] neg_hi:[0,1]
	s_nop 0
	v_pk_fma_f32 v[204:205], v[66:67], s[82:83], v[82:83] op_sel_hi:[1,0,1]
	s_waitcnt lgkmcnt(4)
	v_pk_add_f32 v[66:67], v[84:85], v[178:179] op_sel_hi:[1,0] neg_lo:[0,1] neg_hi:[0,1]
	v_max3_f32 v82, v90, v204, v205
	v_pk_fma_f32 v[208:209], v[68:69], s[82:83], v[66:67] op_sel_hi:[1,0,1]
	s_waitcnt lgkmcnt(2)
	v_pk_add_f32 v[66:67], v[86:87], v[178:179] op_sel_hi:[1,0] neg_lo:[0,1] neg_hi:[0,1]
	v_max3_f32 v68, v82, v208, v209
	v_pk_fma_f32 v[210:211], v[70:71], s[82:83], v[66:67] op_sel_hi:[1,0,1]
	s_waitcnt lgkmcnt(0)
	v_pk_add_f32 v[66:67], v[88:89], v[178:179] op_sel_hi:[1,0] neg_lo:[0,1] neg_hi:[0,1]
	v_max3_f32 v68, v68, v210, v211
	v_pk_fma_f32 v[212:213], v[72:73], s[82:83], v[66:67] op_sel_hi:[1,0,1]
	v_add_u32_e32 v66, 0x1d0, v0
	v_max3_f32 v82, v68, v212, v213
	v_add_u32_e32 v67, 0x1cf, v0
	v_add_u32_e32 v68, 0x1ce, v0
	v_add_u32_e32 v69, 0x1cd, v0
	v_add_u32_e32 v70, 0x1cc, v0
	v_add_u32_e32 v71, 0x1cb, v0
	v_add_u32_e32 v72, 0x1ca, v0
	v_and_b32_e32 v66, 0x1ff, v66
	v_and_b32_e32 v67, 0x1ff, v67
	v_and_b32_e32 v68, 0x1ff, v68
	v_and_b32_e32 v69, 0x1ff, v69
	v_and_b32_e32 v70, 0x1ff, v70
	v_and_b32_e32 v71, 0x1ff, v71
	v_and_b32_e32 v72, 0x1ff, v72
	v_add_u32_e32 v0, 0x1c9, v0
	v_lshl_add_u32 v66, v66, 2, s4
	v_lshl_add_u32 v67, v67, 2, s4
	v_lshl_add_u32 v68, v68, 2, s4
	v_lshl_add_u32 v69, v69, 2, s4
	v_lshl_add_u32 v70, v70, 2, s4
	v_lshl_add_u32 v71, v71, 2, s4
	v_lshl_add_u32 v72, v72, 2, s4
	v_and_b32_e32 v0, 0x1ff, v0
	v_lshl_add_u32 v0, v0, 2, s4
	ds_read_b32 v66, v66
	ds_read_b32 v67, v67
	ds_read_b32 v68, v68
	ds_read_b32 v69, v69
	ds_read_b32 v70, v70
	ds_read_b32 v71, v71
	ds_read_b32 v72, v72
	ds_read_b32 v73, v0
	s_waitcnt lgkmcnt(6)
	v_pk_add_f32 v[66:67], v[66:67], v[178:179] op_sel_hi:[1,0] neg_lo:[0,1] neg_hi:[0,1]
	s_nop 0
	v_pk_fma_f32 v[214:215], v[74:75], s[82:83], v[66:67] op_sel_hi:[1,0,1]
	s_waitcnt lgkmcnt(4)
	v_pk_add_f32 v[66:67], v[68:69], v[178:179] op_sel_hi:[1,0] neg_lo:[0,1] neg_hi:[0,1]
	v_max3_f32 v0, v82, v214, v215
	v_pk_fma_f32 v[216:217], v[76:77], s[82:83], v[66:67] op_sel_hi:[1,0,1]
	s_waitcnt lgkmcnt(2)
	v_pk_add_f32 v[66:67], v[70:71], v[178:179] op_sel_hi:[1,0] neg_lo:[0,1] neg_hi:[0,1]
	v_max3_f32 v0, v0, v216, v217
	v_pk_fma_f32 v[218:219], v[78:79], s[82:83], v[66:67] op_sel_hi:[1,0,1]
	s_waitcnt lgkmcnt(0)
	v_pk_add_f32 v[66:67], v[72:73], v[178:179] op_sel_hi:[1,0] neg_lo:[0,1] neg_hi:[0,1]
	v_max3_f32 v0, v0, v218, v219
	v_pk_fma_f32 v[220:221], v[80:81], s[82:83], v[66:67] op_sel_hi:[1,0,1]
	s_nop 0
	v_max3_f32 v243, v0, v220, v221

.Lwl_skip1:
	s_or_b64 exec, exec, s[12:13]
	s_cmp_ge_u32 s27, s22
	s_cbranch_scc1 .LBB0_372
	s_bitcmp1_b32 s27, 0
	s_cselect_b32 s98, 0x6c00, 0
	v_add_u32_e32 v204, s98, v239
	s_waitcnt vmcnt(2)
	ds_write_b128 v204, v[126:129]
	v_add_u32_e32 v204, s98, v234
	v_add_u32_e32 v205, v204, v235
	v_add_u32_e32 v204, v204, v237
	s_cmp_ge_u32 s26, s21
	s_waitcnt vmcnt(1)
	ds_write_b128 v205, v[118:121] offset:9216
	s_waitcnt vmcnt(0)
	ds_write_b128 v204, v[114:117] offset:9216
	s_cbranch_scc1 .LBB0_372
	v_add_u32_e32 v204, s94, v231
	v_add_u32_e32 v204, 0x100, v204
	v_mad_i64_i32 v[206:207], s[98:99], v204, s87, v[168:169]
	v_lshl_add_u64 v[208:209], s[94:95], 1, v[170:171]
	v_lshl_add_u64 v[210:211], v[208:209], 0, v[172:173]
	global_load_dwordx4 v[126:129], v[206:207], off offset:2048
	global_load_dwordx4 v[118:121], v[210:211], off offset:512
	v_lshl_add_u64 v[206:207], v[208:209], 0, v[174:175]
	global_load_dwordx4 v[114:117], v[206:207], off offset:512
	s_branch .LBB0_372
.Lwl_skip2:
	s_or_b64 exec, exec, s[10:11]
	s_cmp_ge_u32 s26, s25
	s_cbranch_scc1 .LBB0_387
	s_bitcmp1_b32 s26, 0
	s_cselect_b32 s98, 0x6c00, 0
	v_add_u32_e32 v204, s98, v239
	s_waitcnt vmcnt(1)
	ds_write_b128 v204, v[138:141]
	v_add_u32_e32 v204, s98, v234
	s_add_i32 s98, s26, 5
	v_add_u32_e32 v205, v204, v235
	v_add_u32_e32 v204, v204, v237
	s_cmp_ge_u32 s98, s22
	ds_write_b128 v205, v[122:125] offset:9216
	s_waitcnt vmcnt(0)
	ds_write_b128 v204, v[130:133] offset:9216
	s_cbranch_scc1 .LBB0_387
	s_add_i32 s98, s94, 0x140
	v_add_u32_e32 v204, s98, v231
	s_mov_b32 s99, s95
	v_mad_i64_i32 v[206:207], s[100:101], v204, s87, v[168:169]
	v_lshl_add_u64 v[208:209], s[98:99], 1, v[170:171]
	v_lshl_add_u64 v[210:211], v[208:209], 0, v[172:173]
	global_load_dwordx4 v[138:141], v[206:207], off offset:2048
	global_load_dwordx4 v[122:125], v[210:211], off
	v_lshl_add_u64 v[206:207], v[208:209], 0, v[174:175]
	global_load_dwordx4 v[130:133], v[206:207], off
	s_branch .LBB0_387
.Lwl_skip3:
	s_or_b64 exec, exec, s[10:11]
	s_cmp_ge_u32 s12, s22
	s_cbranch_scc1 .LBB0_400
	s_bitcmp1_b32 s12, 0
	s_cselect_b32 s98, 0x6c00, 0
	v_add_u32_e32 v204, s98, v239
	s_waitcnt vmcnt(0)
	ds_write_b128 v204, v[142:145]
	v_add_u32_e32 v204, s98, v234
	s_add_i32 s98, s26, 6
	v_add_u32_e32 v205, v204, v235
	v_add_u32_e32 v204, v204, v237
	s_cmp_ge_u32 s98, s22
	ds_write_b128 v205, v[134:137] offset:9216
	ds_write_b128 v204, v[146:149] offset:9216
	s_cbranch_scc1 .LBB0_400
	s_add_i32 s98, s94, 0x180
	v_add_u32_e32 v204, s98, v231
	s_mov_b32 s99, s95
	v_mad_i64_i32 v[206:207], s[100:101], v204, s87, v[168:169]
	v_lshl_add_u64 v[208:209], s[98:99], 1, v[170:171]
	v_lshl_add_u64 v[210:211], v[208:209], 0, v[172:173]
	global_load_dwordx4 v[142:145], v[206:207], off offset:2048
	global_load_dwordx4 v[134:137], v[210:211], off
	v_lshl_add_u64 v[206:207], v[208:209], 0, v[174:175]
	global_load_dwordx4 v[146:149], v[206:207], off
	s_branch .LBB0_400
.LBB0_375:
.LBB0_378:
	s_add_i32 s0, s94, 64
	v_cmp_le_i32_e32 vcc, s0, v229
	s_and_saveexec_b64 s[10:11], vcc
	s_cbranch_execz .Lwl_skip2
	s_bitcmp1_b32 s27, 0
	s_cselect_b32 s0, 0x6c00, 0
	s_add_i32 s0, s0, 0
	v_add_u32_e32 v0, s0, v232
	v_add_u32_e32 v180, v0, v238
	ds_read_b128 v[66:69], v180
	ds_read_b128 v[150:153], v180 offset:32
	ds_read_b128 v[70:73], v180 offset:4608
	ds_read_b128 v[154:157], v180 offset:4640
	s_waitcnt lgkmcnt(3)
	v_mfma_f32_32x32x16_bf16 v[82:97], v[66:69], v[98:101], 0
	s_waitcnt lgkmcnt(1)
	v_mfma_f32_32x32x16_bf16 v[66:81], v[70:73], v[98:101], 0
	v_mfma_f32_32x32x16_bf16 v[82:97], v[150:153], v[102:105], v[82:97]
	ds_read_b128 v[150:153], v180 offset:64
	ds_read_b128 v[158:161], v180 offset:96
	ds_read_b128 v[162:165], v180 offset:4672
	ds_read_b128 v[180:183], v180 offset:4704
	s_waitcnt lgkmcnt(4)
	v_mfma_f32_32x32x16_bf16 v[66:81], v[154:157], v[102:105], v[66:81]
	s_waitcnt lgkmcnt(3)
	v_mfma_f32_32x32x16_bf16 v[82:97], v[150:153], v[106:109], v[82:97]
	v_add_u32_e32 v242, v0, v233
	s_waitcnt lgkmcnt(1)
	v_mfma_f32_32x32x16_bf16 v[66:81], v[162:165], v[106:109], v[66:81]
	v_mfma_f32_32x32x16_bf16 v[82:97], v[158:161], v[110:113], v[82:97]
	ds_read_b128 v[162:165], v242 offset:9216
	ds_read_b128 v[158:161], v242 offset:13824
	ds_read_b128 v[154:157], v242 offset:18432
	ds_read_b128 v[150:153], v242 offset:23040
	s_waitcnt lgkmcnt(4)
	v_mfma_f32_32x32x16_bf16 v[66:81], v[180:183], v[110:113], v[66:81]
	s_cmp_ge_u32 s26, s25
	s_cbranch_scc1 .Lwl_q2
	s_bitcmp1_b32 s26, 0
	s_cselect_b32 s98, 0x6c00, 0
	v_add_u32_e32 v204, s98, v239
	s_waitcnt vmcnt(1)
	ds_write_b128 v204, v[138:141]
	v_add_u32_e32 v204, s98, v234
	s_add_i32 s98, s26, 5
	v_add_u32_e32 v205, v204, v235
	v_add_u32_e32 v204, v204, v237
	s_cmp_ge_u32 s98, s22
	ds_write_b128 v205, v[122:125] offset:9216
	s_waitcnt vmcnt(0)
	ds_write_b128 v204, v[130:133] offset:9216
	s_cbranch_scc1 .Lwl_q2
	s_add_i32 s98, s94, 0x140
	v_add_u32_e32 v204, s98, v231
	s_mov_b32 s99, s95
	v_mad_i64_i32 v[206:207], s[100:101], v204, s87, v[168:169]
	v_lshl_add_u64 v[208:209], s[98:99], 1, v[170:171]
	v_lshl_add_u64 v[210:211], v[208:209], 0, v[172:173]
	global_load_dwordx4 v[138:141], v[206:207], off offset:2048
	global_load_dwordx4 v[122:125], v[210:211], off
	v_lshl_add_u64 v[206:207], v[208:209], 0, v[174:175]
	global_load_dwordx4 v[130:133], v[206:207], off
.Lwl_q2:
	s_movk_i32 s0, 0x7f
	v_add_u32_e32 v180, 64, v240
	v_add3_u32 v0, v236, v240, s0
	v_cmp_gt_i32_e32 vcc, s85, v180
	s_and_saveexec_b64 s[0:1], vcc
	s_xor_b64 s[0:1], exec, s[0:1]
	s_cbranch_execnz .LBB0_383
	s_andn2_saveexec_b64 s[0:1], s[0:1]
	s_cbranch_execnz .LBB0_384

.LBB0_388:
.LBB0_391:
	s_add_i32 s0, s94, 0x80
	v_cmp_le_i32_e32 vcc, s0, v229
	s_and_saveexec_b64 s[10:11], vcc
	s_cbranch_execz .Lwl_skip3
	s_bitcmp1_b32 s26, 0
	s_cselect_b32 s0, 0x6c00, 0
	s_add_i32 s0, s0, 0
	v_add_u32_e32 v0, s0, v232
	v_add_u32_e32 v180, v0, v238
	ds_read_b128 v[66:69], v180
	ds_read_b128 v[150:153], v180 offset:32
	ds_read_b128 v[70:73], v180 offset:4608
	ds_read_b128 v[154:157], v180 offset:4640
	s_waitcnt lgkmcnt(3)
	v_mfma_f32_32x32x16_bf16 v[82:97], v[66:69], v[98:101], 0
	s_waitcnt lgkmcnt(1)
	v_mfma_f32_32x32x16_bf16 v[66:81], v[70:73], v[98:101], 0
	v_mfma_f32_32x32x16_bf16 v[82:97], v[150:153], v[102:105], v[82:97]
	ds_read_b128 v[150:153], v180 offset:64
	ds_read_b128 v[158:161], v180 offset:96
	ds_read_b128 v[162:165], v180 offset:4672
	ds_read_b128 v[180:183], v180 offset:4704
	s_waitcnt lgkmcnt(4)
	v_mfma_f32_32x32x16_bf16 v[66:81], v[154:157], v[102:105], v[66:81]
	s_waitcnt lgkmcnt(3)
	v_mfma_f32_32x32x16_bf16 v[82:97], v[150:153], v[106:109], v[82:97]
	v_add_u32_e32 v242, v0, v233
	s_waitcnt lgkmcnt(1)
	v_mfma_f32_32x32x16_bf16 v[66:81], v[162:165], v[106:109], v[66:81]
	v_mfma_f32_32x32x16_bf16 v[82:97], v[158:161], v[110:113], v[82:97]
	ds_read_b128 v[162:165], v242 offset:9216
	ds_read_b128 v[158:161], v242 offset:13824
	ds_read_b128 v[154:157], v242 offset:18432
	ds_read_b128 v[150:153], v242 offset:23040
	s_waitcnt lgkmcnt(4)
	v_mfma_f32_32x32x16_bf16 v[66:81], v[180:183], v[110:113], v[66:81]
	s_cmp_ge_u32 s12, s22
	s_cbranch_scc1 .Lwl_q3
	s_bitcmp1_b32 s12, 0
	s_cselect_b32 s98, 0x6c00, 0
	v_add_u32_e32 v204, s98, v239
	s_waitcnt vmcnt(0)
	ds_write_b128 v204, v[142:145]
	v_add_u32_e32 v204, s98, v234
	s_add_i32 s98, s26, 6
	v_add_u32_e32 v205, v204, v235
	v_add_u32_e32 v204, v204, v237
	s_cmp_ge_u32 s98, s22
	ds_write_b128 v205, v[134:137] offset:9216
	ds_write_b128 v204, v[146:149] offset:9216
	s_cbranch_scc1 .Lwl_q3
	s_add_i32 s98, s94, 0x180
	v_add_u32_e32 v204, s98, v231
	s_mov_b32 s99, s95
	v_mad_i64_i32 v[206:207], s[100:101], v204, s87, v[168:169]
	v_lshl_add_u64 v[208:209], s[98:99], 1, v[170:171]
	v_lshl_add_u64 v[210:211], v[208:209], 0, v[172:173]
	global_load_dwordx4 v[142:145], v[206:207], off offset:2048
	global_load_dwordx4 v[134:137], v[210:211], off
	v_lshl_add_u64 v[206:207], v[208:209], 0, v[174:175]
	global_load_dwordx4 v[146:149], v[206:207], off
.Lwl_q3:
	v_add3_u32 v0, v236, v240, 63
	v_cmp_gt_i32_e32 vcc, s85, v240
	s_and_saveexec_b64 s[0:1], vcc
	s_xor_b64 s[0:1], exec, s[0:1]
	s_cbranch_execnz .LBB0_396
	s_andn2_saveexec_b64 s[0:1], s[0:1]
	s_cbranch_execnz .LBB0_397

	.amdhsa_kernel _Z14fwd_megakernel6Params
		.amdhsa_group_segment_fixed_size 0
		.amdhsa_private_segment_fixed_size 0
		.amdhsa_kernarg_size 416
		.amdhsa_user_sgpr_count 2
		.amdhsa_user_sgpr_dispatch_ptr 0
		.amdhsa_user_sgpr_queue_ptr 0
		.amdhsa_user_sgpr_kernarg_segment_ptr 1
		.amdhsa_user_sgpr_dispatch_id 0
		.amdhsa_user_sgpr_kernarg_preload_length 0
		.amdhsa_user_sgpr_kernarg_preload_offset 0
		.amdhsa_user_sgpr_private_segment_size 0
		.amdhsa_uses_dynamic_stack 0
		.amdhsa_enable_private_segment 0
		.amdhsa_system_sgpr_workgroup_id_x 1
		.amdhsa_system_sgpr_workgroup_id_y 0
		.amdhsa_system_sgpr_workgroup_id_z 0
		.amdhsa_system_sgpr_workgroup_info 0
		.amdhsa_system_vgpr_workitem_id 2
		.amdhsa_next_free_vgpr 256
		.amdhsa_next_free_sgpr 102
		.amdhsa_accum_offset 256
		.amdhsa_reserve_vcc 1
		.amdhsa_float_round_mode_32 0
		.amdhsa_float_round_mode_16_64 0
		.amdhsa_float_denorm_mode_32 3
		.amdhsa_float_denorm_mode_16_64 3
		.amdhsa_dx10_clamp 1
		.amdhsa_ieee_mode 1
		.amdhsa_fp16_overflow 0
		.amdhsa_tg_split 0
		.amdhsa_exception_fp_ieee_invalid_op 0
		.amdhsa_exception_fp_denorm_src 0
		.amdhsa_exception_fp_ieee_div_zero 0
		.amdhsa_exception_fp_ieee_overflow 0
		.amdhsa_exception_fp_ieee_underflow 0
		.amdhsa_exception_fp_ieee_inexact 0
		.amdhsa_exception_int_div_zero 0
	.end_amdhsa_kernel

amdhsa.kernels:
  - .agpr_count:     0
    .args:
      - .offset:         0
        .size:           160
        .value_kind:     by_value
      - .offset:         160
        .size:           4
        .value_kind:     hidden_block_count_x
      - .offset:         164
        .size:           4
        .value_kind:     hidden_block_count_y
      - .offset:         168
        .size:           4
        .value_kind:     hidden_block_count_z
      - .offset:         172
        .size:           2
        .value_kind:     hidden_group_size_x
      - .offset:         174
        .size:           2
        .value_kind:     hidden_group_size_y
      - .offset:         176
        .size:           2
        .value_kind:     hidden_group_size_z
      - .offset:         178
        .size:           2
        .value_kind:     hidden_remainder_x
      - .offset:         180
        .size:           2
        .value_kind:     hidden_remainder_y
      - .offset:         182
        .size:           2
        .value_kind:     hidden_remainder_z
      - .offset:         200
        .size:           8
        .value_kind:     hidden_global_offset_x
      - .offset:         208
        .size:           8
        .value_kind:     hidden_global_offset_y
      - .offset:         216
        .size:           8
        .value_kind:     hidden_global_offset_z
      - .offset:         224
        .size:           2
        .value_kind:     hidden_grid_dims
      - .offset:         248
        .size:           8
        .value_kind:     hidden_multigrid_sync_arg
      - .offset:         280
        .size:           4
        .value_kind:     hidden_dynamic_lds_size
    .group_segment_fixed_size: 0
    .kernarg_segment_align: 8
    .kernarg_segment_size: 416
    .language:       OpenCL C
    .language_version:
      - 2
      - 0
    .max_flat_workgroup_size: 512
    .name:           _Z14fwd_megakernel6Params
    .private_segment_fixed_size: 0
    .sgpr_count:     108
    .sgpr_spill_count: 125
    .symbol:         _Z14fwd_megakernel6Params.kd
    .uniform_work_group_size: 1
    .uses_dynamic_stack: false
    .vgpr_count:     256
    .vgpr_spill_count: 0
    .wavefront_size: 64
